# v43 + attention exp packing + ret_sample wave_sum + attn_sample reductions/PV + ret_out jt hoist, with never-executed padding so every GEMM main loop sits at the same 64-byte phase as in v43
# baseline (speedup 1.0000x reference)
; DEV int tidx() { int t = threadIdx.x; asm volatile("" : "+v"(t)); return t; }
; DEV float log_gamma(int h) { return log1pf(-exp2f(-5.0f - (float)h)); }
; DEV void ret_out_item(const Params& p, int l, int item, unsigned char* smem) {
;   const int bh = item >> 5, n = item & 31, b = bh >> 2, h = bh & 3;
;   bf16_t* Z = (bf16_t*)(p.ws + WS_Z);
;   const bf16_t* Sb = (const bf16_t*)(p.ws + WS_H + 16777216) + (size_t)(bh * 32 + n) * 8192;
;   unsigned char* Qs = smem;
;   unsigned char* Ks = smem + 18432;
;   bf16_t* Vt = (bf16_t*)(smem + 36864);
;   bf16_t* Gs = (bf16_t*)(smem + 71680);
;   const int tid = tidx(), lane = tid & 63, w = tid >> 6, fr = lane & 15, fq = lane >> 4;
;   const size_t rowbase = (size_t)b * SEQ + n * 128;
;   const float lg = log_gamma(h);
;   {
;     u32x4 q[2], k[2], v[4], g[4];
; #pragma unroll
;     for (int i = 0; i < 2; ++i) {
;       const int c = tid + i * 512, r = c >> 3, kc = c & 7;
;       q[i] = *(const u32x4*)(Z + (rowbase + r) * NIN + RQ + h * 64 + kc * 8);
;       k[i] = *(const u32x4*)(Z + (rowbase + r) * NIN + RK + h * 64 + kc * 8);
;     }
; #pragma unroll
;     for (int i = 0; i < 4; ++i) {
;       const int c = tid + i * 512;
;       v[i] = *(const u32x4*)(Z + (rowbase + (c & 127)) * NIN + RV + h * 128 + (c >> 7) * 8);
;       g[i] = *(const u32x4*)(Z + (rowbase + (c >> 4)) * NIN + RG + h * 128 + (c & 15) * 8);
;     }
.LBB0_85:
	s_ashr_i32 s0, s18, 7
	s_ashr_i32 s1, s0, 31
	s_bfe_u32 s4, s18, 0x20005
	s_lshl_b64 s[38:39], s[0:1], 12
	s_lshl_b32 s0, s18, 7
	s_and_b32 s0, s0, 0xf80
	v_cvt_f32_ubyte0_e32 v0, s4
	s_or_b32 s38, s38, s0
	v_sub_f32_e32 v0, 0xc0a00000, v0
	s_mov_b32 s0, 0xc2fc0000
	v_cmp_gt_f32_e32 vcc, s0, v0
	s_ashr_i32 s19, s18, 31
	s_lshl_b64 s[2:3], s[18:19], 14
	s_waitcnt lgkmcnt(0)
	v_cndmask_b32_e32 v1, 0, v203, vcc
	v_add_f32_e32 v0, v0, v1
	v_exp_f32_e32 v0, v0
	s_and_b64 s[0:1], vcc, exec
	s_cselect_b32 s0, 0xffffffc0, 0
	v_mov_b32_e32 v44, v171
	v_ldexp_f32 v33, v0, s0
	v_sub_f32_e32 v2, 1.0, v33
	v_add_f32_e32 v0, -1.0, v2
	v_sub_f32_e32 v1, v0, v2
	v_add_f32_e32 v1, 1.0, v1
	v_sub_f32_e64 v0, -v33, v0
	v_add_f32_e32 v3, v0, v1
	v_frexp_mant_f32_e32 v0, v2
	s_mov_b32 s0, 0x3f2aaaab
	v_cmp_gt_f32_e32 vcc, s0, v0
	v_cvt_f64_f32_e32 v[0:1], v2
	v_frexp_exp_i32_f64_e32 v0, v[0:1]
	v_subbrev_co_u32_e32 v0, vcc, 0, v0, vcc
	v_sub_u32_e32 v1, 0, v0
	v_ldexp_f32 v2, v2, v1
	v_ldexp_f32 v1, v3, v1
	v_add_f32_e32 v3, -1.0, v2
	v_add_f32_e32 v4, 1.0, v3
	v_sub_f32_e32 v4, v2, v4
	v_add_f32_e32 v4, v1, v4
	v_add_f32_e32 v5, v3, v4
	v_sub_f32_e32 v3, v5, v3
	v_sub_f32_e32 v3, v4, v3
	v_add_f32_e32 v4, 1.0, v2
	v_add_f32_e32 v6, -1.0, v4
	v_sub_f32_e32 v2, v2, v6
	v_add_f32_e32 v1, v1, v2
	v_add_f32_e32 v2, v4, v1
	v_sub_f32_e32 v4, v2, v4
	v_sub_f32_e32 v1, v1, v4
	v_rcp_f32_e32 v4, v2
	v_cvt_f32_i32_e32 v0, v0
	s_mov_b32 s0, 0x3f317218
	v_mul_f32_e32 v6, v5, v4
	v_mul_f32_e32 v7, v2, v6
	v_fma_f32 v8, v6, v2, -v7
	v_fmac_f32_e32 v8, v6, v1
	v_add_f32_e32 v9, v7, v8
	v_sub_f32_e32 v10, v5, v9
	v_sub_f32_e32 v5, v5, v10
	v_sub_f32_e32 v7, v9, v7
	v_sub_f32_e32 v5, v5, v9
	v_add_f32_e32 v3, v3, v5
	v_sub_f32_e32 v5, v7, v8
	v_add_f32_e32 v3, v5, v3
	v_add_f32_e32 v5, v10, v3
	v_mul_f32_e32 v7, v4, v5
	v_mul_f32_e32 v8, v2, v7
	v_fma_f32 v2, v7, v2, -v8
	v_fmac_f32_e32 v2, v7, v1
	v_sub_f32_e32 v1, v10, v5
	v_add_f32_e32 v1, v3, v1
	v_add_f32_e32 v3, v8, v2
	v_sub_f32_e32 v9, v5, v3
	v_sub_f32_e32 v5, v5, v9
	v_sub_f32_e32 v8, v3, v8
	v_sub_f32_e32 v3, v5, v3
	v_add_f32_e32 v1, v1, v3
	v_sub_f32_e32 v2, v8, v2
	v_add_f32_e32 v1, v2, v1
	v_add_f32_e32 v2, v6, v7
	v_add_f32_e32 v1, v9, v1
	v_sub_f32_e32 v3, v2, v6
	v_mul_f32_e32 v1, v4, v1
	v_sub_f32_e32 v3, v7, v3
	v_add_f32_e32 v1, v3, v1
	v_mul_f32_e32 v6, 0x3f317218, v0
	v_add_f32_e32 v3, v2, v1
	v_fma_f32 v7, v0, s0, -v6
	v_mul_f32_e32 v4, v3, v3
	v_fmac_f32_e32 v7, 0xb102e308, v0
	v_sub_f32_e32 v0, v3, v2
	v_fmamk_f32 v5, v4, 0x3e9b6dac, v201
	v_sub_f32_e32 v0, v1, v0
	v_add_f32_e32 v1, v6, v7
	v_fmaak_f32 v5, v4, v5, 0x3f2aaada
	v_sub_f32_e32 v2, v1, v6
	v_ldexp_f32 v6, v3, 1
	v_mul_f32_e32 v3, v3, v4
	v_mul_f32_e32 v3, v3, v5
	v_add_f32_e32 v4, v6, v3
	v_sub_f32_e32 v5, v4, v6
	v_ldexp_f32 v0, v0, 1
	v_sub_f32_e32 v3, v3, v5
	v_add_f32_e32 v0, v0, v3
	v_add_f32_e32 v3, v4, v0
	v_sub_f32_e32 v4, v3, v4
	v_sub_f32_e32 v0, v0, v4
	v_add_f32_e32 v4, v1, v3
	v_sub_f32_e32 v5, v4, v1
	v_sub_f32_e32 v6, v4, v5
	v_sub_f32_e32 v2, v7, v2
	v_sub_f32_e32 v1, v1, v6
	v_sub_f32_e32 v3, v3, v5
	v_add_f32_e32 v1, v3, v1
	v_add_f32_e32 v3, v2, v0
	v_sub_f32_e32 v5, v3, v2
	v_sub_f32_e32 v6, v3, v5
	v_add_f32_e32 v1, v3, v1
	v_sub_f32_e32 v2, v2, v6
	v_sub_f32_e32 v0, v0, v5
	v_add_f32_e32 v5, v4, v1
	v_add_f32_e32 v0, v0, v2
	v_sub_f32_e32 v2, v5, v4
	v_ashrrev_i32_e32 v16, 3, v44
	v_sub_f32_e32 v1, v1, v2
	v_ashrrev_i32_e32 v17, 31, v16
	v_add_f32_e32 v4, v0, v1
	s_mov_b32 s0, 0x33800000
	v_lshl_add_u64 v[0:1], s[38:39], 0, v[16:17]
	v_mov_b64_e32 v[12:13], s[30:31]
	v_cmp_gt_f32_e32 vcc, s0, v33
	v_mad_u64_u32 v[2:3], s[0:1], v0, s95, v[12:13]
	v_mad_i32_i24 v3, v1, s95, v3
	s_lshl_b32 s6, s4, 7
	v_lshl_add_u64 v[0:1], v[2:3], 0, s[6:7]
	v_lshlrev_b32_e32 v2, 4, v44
	v_add_u32_e32 v7, 0x200, v44
	v_and_b32_e32 v168, 0x70, v2
	v_ashrrev_i32_e32 v18, 3, v7
	v_lshl_add_u64 v[0:1], v[0:1], 0, v[168:169]
	v_ashrrev_i32_e32 v19, 31, v18
	global_load_dwordx4 v[48:51], v[0:1], off
	global_load_dwordx4 v[52:55], v[0:1], off offset:512
	v_lshl_add_u64 v[0:1], s[38:39], 0, v[18:19]
	v_mad_u64_u32 v[2:3], s[0:1], v0, s95, v[12:13]
	v_mad_i32_i24 v3, v1, s95, v3
	v_lshl_add_u64 v[0:1], v[2:3], 0, s[6:7]
	v_lshl_add_u64 v[0:1], v[0:1], 0, v[168:169]
	global_load_dwordx4 v[56:59], v[0:1], off
	global_load_dwordx4 v[60:63], v[0:1], off offset:512
	v_add_f32_e32 v0, v5, v4
	v_cmp_nlt_f32_e64 s[0:1], 1.0, v33
	v_and_b32_e32 v32, 0x7f, v44
	v_add_u32_e32 v8, 0x400, v44
	v_cndmask_b32_e64 v0, v204, v0, s[0:1]
	v_cmp_neq_f32_e64 s[0:1], 1.0, v33
	v_add_u32_e32 v17, 0x600, v44
	v_ashrrev_i32_e32 v40, 4, v44
	v_cndmask_b32_e64 v46, v205, v0, s[0:1]
	v_or_b32_e32 v0, s38, v32
	v_mad_u64_u32 v[0:1], s[0:1], v0, s95, v[12:13]
	v_ashrrev_i32_e32 v20, 4, v7
	v_ashrrev_i32_e32 v22, 4, v8
	v_ashrrev_i32_e32 v24, 4, v17
	v_lshlrev_b32_e32 v6, 3, v44
	v_mad_i32_i24 v1, s39, v206, v1
	s_lshl_b32 s0, s4, 8
	s_mov_b32 s1, s7
	v_and_b32_e32 v64, -8, v40
	v_and_b32_e32 v26, -8, v20
	v_and_b32_e32 v28, -8, v22
	v_and_b32_e32 v30, -8, v24
	v_lshl_add_u64 v[14:15], v[0:1], 0, s[0:1]
	v_and_b32_e32 v4, 0x78, v6
	v_ashrrev_i32_e32 v65, 31, v64
	v_ashrrev_i32_e32 v41, 31, v40
	v_ashrrev_i32_e32 v27, 31, v26
	v_ashrrev_i32_e32 v21, 31, v20
	v_ashrrev_i32_e32 v29, 31, v28
	v_ashrrev_i32_e32 v23, 31, v22
	v_ashrrev_i32_e32 v31, 31, v30
	v_ashrrev_i32_e32 v25, 31, v24
	v_lshl_add_u64 v[42:43], v[64:65], 1, v[14:15]
	v_lshl_add_u64 v[0:1], s[38:39], 0, v[40:41]
	v_lshlrev_b32_e32 v76, 1, v4
	v_lshl_add_u64 v[38:39], v[26:27], 1, v[14:15]
	v_lshl_add_u64 v[4:5], s[38:39], 0, v[20:21]
	v_lshl_add_u64 v[36:37], v[28:29], 1, v[14:15]
; DEV void ret_out_item(const Params& p, int l, int item, unsigned char* smem) {
;     ...
;   {
;     u32x4 q[2], k[2], v[4], g[4];
; #pragma unroll
;     for (int i = 0; i < 2; ++i) {
;       const int c = tid + i * 512, r = c >> 3, kc = c & 7;
;       q[i] = *(const u32x4*)(Z + (rowbase + r) * NIN + RQ + h * 64 + kc * 8);
;       k[i] = *(const u32x4*)(Z + (rowbase + r) * NIN + RK + h * 64 + kc * 8);
;     }
; #pragma unroll
;     for (int i = 0; i < 4; ++i) {
;       const int c = tid + i * 512;
;       v[i] = *(const u32x4*)(Z + (rowbase + (c & 127)) * NIN + RV + h * 128 + (c >> 7) * 8);
;       g[i] = *(const u32x4*)(Z + (rowbase + (c >> 4)) * NIN + RG + h * 128 + (c & 15) * 8);
;     }
; #pragma unroll
;     for (int i = 0; i < 2; ++i) {
;       const int c = tid + i * 512, r = c >> 3, kc = c & 7;
;       *(u32x4*)(Qs + r * 144 + kc * 16) = q[i];
;       *(u32x4*)(Ks + r * 144 + kc * 16) = k[i];
;     }
; #pragma unroll
;     for (int i = 0; i < 4; ++i) {
;       const int c = tid + i * 512, r = c & 127, kc = c >> 7;
;       bf16_t* dst = Vt + (kc * 8) * 136 + r;
;       dst[0 * 136] = (bf16_t)(v[i].x & 0xffff); dst[1 * 136] = (bf16_t)(v[i].x >> 16);
;       dst[2 * 136] = (bf16_t)(v[i].y & 0xffff); dst[3 * 136] = (bf16_t)(v[i].y >> 16);
;       dst[4 * 136] = (bf16_t)(v[i].z & 0xffff); dst[5 * 136] = (bf16_t)(v[i].z >> 16);
;       dst[6 * 136] = (bf16_t)(v[i].w & 0xffff); dst[7 * 136] = (bf16_t)(v[i].w >> 16);
;       *(u32x4*)(Gs + (c >> 4) * 136 + (c & 15) * 8) = g[i];
;     }
; #pragma unroll
;     for (int i = 0; i < 2; ++i) {
;       const int c = tid + i * 512, r = c >> 3, kc = c & 7;
;       *(u32x4*)(smem + 106496 + r * 144 + kc * 16) = *(const u32x4*)(Sb + r * 64 + kc * 8);
;     }
;   }
;   __syncthreads();
	v_lshl_add_u64 v[8:9], s[38:39], 0, v[22:23]
	v_lshl_add_u64 v[34:35], v[30:31], 1, v[14:15]
	v_lshl_add_u64 v[14:15], s[38:39], 0, v[24:25]
	v_mad_u64_u32 v[2:3], s[4:5], v0, s95, v[12:13]
	v_mad_u64_u32 v[6:7], s[4:5], v4, s95, v[12:13]
	v_mad_u64_u32 v[10:11], s[4:5], v8, s95, v[12:13]
	v_mad_u64_u32 v[12:13], s[4:5], v14, s95, v[12:13]
	v_mad_i32_i24 v3, v1, s95, v3
	v_mad_i32_i24 v7, v5, s95, v7
	v_mad_i32_i24 v11, v9, s95, v11
	v_mad_i32_i24 v13, v15, s95, v13
	v_lshl_add_u64 v[0:1], v[2:3], 0, s[0:1]
	v_mov_b32_e32 v77, v169
	v_lshl_add_u64 v[4:5], v[6:7], 0, s[0:1]
	v_lshl_add_u64 v[8:9], v[10:11], 0, s[0:1]
	v_lshl_add_u64 v[12:13], v[12:13], 0, s[0:1]
	v_add_u32_e32 v21, 0, v168
	v_mul_lo_u32 v19, v16, s33
	v_lshl_add_u64 v[0:1], v[0:1], 0, v[76:77]
	v_lshl_add_u64 v[4:5], v[4:5], 0, v[76:77]
	v_lshl_add_u64 v[8:9], v[8:9], 0, v[76:77]
	v_lshl_add_u64 v[12:13], v[12:13], 0, v[76:77]
	v_add_u32_e32 v17, v21, v19
	global_load_dwordx4 v[0:3], v[0:1], off offset:2048
	s_add_u32 s0, s8, s2
	global_load_dwordx4 v[4:7], v[4:5], off offset:2048
	v_lshl_add_u32 v32, v32, 1, 0
	global_load_dwordx4 v[8:11], v[8:9], off offset:2048
	s_addc_u32 s1, s9, s3
	global_load_dwordx4 v[12:15], v[12:13], off offset:2048
	global_load_dwordx4 v[96:99], v[42:43], off offset:1024
	global_load_dwordx4 v[100:103], v[38:39], off offset:1024
	global_load_dwordx4 v[104:107], v[36:37], off offset:1024
	global_load_dwordx4 v[108:111], v[34:35], off offset:1024
	v_lshlrev_b32_e32 v112, 6, v16
	v_lshl_add_u64 v[114:115], s[0:1], 0, v[168:169]
	v_ashrrev_i32_e32 v113, 31, v112
	v_lshlrev_b32_e32 v120, 6, v18
	v_lshl_add_u64 v[112:113], v[112:113], 1, v[114:115]
	v_ashrrev_i32_e32 v121, 31, v120
	global_load_dwordx4 v[116:119], v[112:113], off
	v_lshl_add_u64 v[120:121], v[120:121], 1, v[114:115]
	global_load_dwordx4 v[124:127], v[120:121], off
	s_waitcnt vmcnt(13)
	ds_write_b128 v17, v[48:51]
	s_waitcnt vmcnt(12)
	ds_write_b128 v17, v[52:55] offset:18432
	v_mul_lo_u32 v17, v18, s33
	v_add_u32_e32 v21, v21, v17
	s_waitcnt vmcnt(11)
	ds_write_b128 v21, v[56:59]
	s_waitcnt vmcnt(10)
	ds_write_b128 v21, v[60:63] offset:18432
	v_mad_u64_u32 v[52:53], s[2:3], v64, s13, v[32:33]
	v_bfe_u32 v79, v44, 4, 2
	v_add_u32_e32 v78, s12, v76
	v_mad_u64_u32 v[42:43], s[2:3], v40, s13, v[78:79]
	v_ashrrev_i32_e32 v45, 6, v44
	v_and_b32_e32 v81, 15, v44
	v_lshlrev_b32_e32 v80, 4, v45
	v_or_b32_e32 v82, v80, v81
	s_movk_i32 s4, 0x110
	v_cndmask_b32_e64 v90, v46, -v33, vcc
	v_cmp_lt_i32_e32 vcc, -1, v45
	v_lshlrev_b32_e32 v83, 2, v79
	s_waitcnt vmcnt(5)
	ds_write_b16 v52, v96 offset:36864
	ds_write_b16_d16_hi v52, v96 offset:37136
	ds_write_b16 v52, v97 offset:37408
	ds_write_b16_d16_hi v52, v97 offset:37680
	ds_write_b16 v52, v98 offset:37952
	ds_write_b16_d16_hi v52, v98 offset:38224
	ds_write_b16 v52, v99 offset:38496
	ds_write_b16_d16_hi v52, v99 offset:38768
	ds_write_b128 v42, v[0:3]
	v_mad_u64_u32 v[0:1], s[2:3], v26, s13, v[32:33]
	s_waitcnt vmcnt(4)
	ds_write_b16 v0, v100 offset:36864
	ds_write_b16_d16_hi v0, v100 offset:37136
	ds_write_b16 v0, v101 offset:37408
	ds_write_b16_d16_hi v0, v101 offset:37680
	ds_write_b16 v0, v102 offset:37952
	ds_write_b16_d16_hi v0, v102 offset:38224
	ds_write_b16 v0, v103 offset:38496
	ds_write_b16_d16_hi v0, v103 offset:38768
	v_mad_u64_u32 v[0:1], s[2:3], v20, s13, v[78:79]
	ds_write_b128 v0, v[4:7]
	v_mad_u64_u32 v[0:1], s[2:3], v28, s13, v[32:33]
	s_waitcnt vmcnt(3)
	ds_write_b16 v0, v104 offset:36864
	ds_write_b16_d16_hi v0, v104 offset:37136
	ds_write_b16 v0, v105 offset:37408
	ds_write_b16_d16_hi v0, v105 offset:37680
	ds_write_b16 v0, v106 offset:37952
	ds_write_b16_d16_hi v0, v106 offset:38224
	ds_write_b16 v0, v107 offset:38496
	ds_write_b16_d16_hi v0, v107 offset:38768
	v_mad_u64_u32 v[0:1], s[2:3], v22, s13, v[78:79]
	ds_write_b128 v0, v[8:11]
	v_mad_u64_u32 v[0:1], s[2:3], v30, s13, v[32:33]
	s_waitcnt vmcnt(2)
	ds_write_b16 v0, v108 offset:36864
	ds_write_b16_d16_hi v0, v108 offset:37136
	ds_write_b16 v0, v109 offset:37408
	ds_write_b16_d16_hi v0, v109 offset:37680
	ds_write_b16 v0, v110 offset:37952
	ds_write_b16_d16_hi v0, v110 offset:38224
	ds_write_b16 v0, v111 offset:38496
	ds_write_b16_d16_hi v0, v111 offset:38768
	v_mad_u64_u32 v[0:1], s[2:3], v24, s13, v[78:79]
	ds_write_b128 v0, v[12:15]
	v_readlane_b32 s0, v248, 16
	v_and_b32_e32 v32, 48, v44
	v_mul_u32_u24_e32 v34, 0x90, v81
	v_add_u32_e32 v6, s0, v168
	v_add_u32_e32 v7, v6, v19
	v_add3_u32 v35, s0, v32, v34
	s_waitcnt vmcnt(1)
	ds_write_b128 v7, v[116:119]
	v_add_u32_e32 v4, v6, v17
	s_waitcnt vmcnt(0)
	ds_write_b128 v4, v[124:127]
	v_mul_lo_u32 v0, v82, s33
	v_add3_u32 v0, 0, v0, v32
	s_waitcnt lgkmcnt(0)
	s_barrier
; DEV f32x4 mfma32(bf16x8 a, bf16x8 b, f32x4 c) { return __builtin_amdgcn_mfma_f32_16x16x32_bf16(a, b, c, 0, 0, 0); }
; DEV void ret_out_item(const Params& p, int l, int item, unsigned char* smem) {
;     ...
;   bf16x8 qf[2];
; #pragma unroll
;   for (int ks = 0; ks < 2; ++ks) qf[ks] = *(const bf16x8*)(Qs + (w * 16 + fr) * 144 + ks * 64 + fq * 16);
;   f32x4 a1[8], a2[8];
; #pragma unroll
;   for (int et = 0; et < 8; ++et) {
;     a1[et] = (f32x4){0.f, 0.f, 0.f, 0.f};
;     a2[et] = (f32x4){0.f, 0.f, 0.f, 0.f};
; #pragma unroll
;     for (int ks = 0; ks < 2; ++ks) {
;       const bf16x8 sf = *(const bf16x8*)(smem + 106496 + (et * 16 + fr) * 144 + ks * 64 + fq * 16);
;       a2[et] = mfma32(qf[ks], sf, a2[et]);
;     }
;   }
;   const int qi = w * 16 + fr;
;   for (int jt = 0; jt <= w; ++jt) {
	ds_read_b128 v[64:67], v0
	ds_read_b128 v[68:71], v0 offset:64
	ds_read_b128 v[0:3], v35
	ds_read_b128 v[128:131], v35 offset:64
	ds_read_b128 v[4:7], v35 offset:2304
	ds_read_b128 v[132:135], v35 offset:2368
	ds_read_b128 v[8:11], v35 offset:4608
	ds_read_b128 v[136:139], v35 offset:4672
	ds_read_b128 v[12:15], v35 offset:6912
	ds_read_b128 v[140:143], v35 offset:6976
	ds_read_b128 v[16:19], v35 offset:9216
	ds_read_b128 v[144:147], v35 offset:9280
	ds_read_b128 v[20:23], v35 offset:11520
	ds_read_b128 v[148:151], v35 offset:11584
	ds_read_b128 v[24:27], v35 offset:13824
	ds_read_b128 v[152:155], v35 offset:13888
	ds_read_b128 v[28:31], v35 offset:16128
	ds_read_b128 v[156:159], v35 offset:16192
	s_waitcnt lgkmcnt(14)
	v_mfma_f32_16x16x32_bf16 v[0:3], v[64:67], v[0:3], 0
	v_mfma_f32_16x16x32_bf16 v[0:3], v[68:71], v[128:131], v[0:3]
	s_waitcnt lgkmcnt(12)
	v_mfma_f32_16x16x32_bf16 v[4:7], v[64:67], v[4:7], 0
	v_mfma_f32_16x16x32_bf16 v[4:7], v[68:71], v[132:135], v[4:7]
	s_waitcnt lgkmcnt(10)
	v_mfma_f32_16x16x32_bf16 v[8:11], v[64:67], v[8:11], 0
	v_mfma_f32_16x16x32_bf16 v[8:11], v[68:71], v[136:139], v[8:11]
	s_waitcnt lgkmcnt(8)
	v_mfma_f32_16x16x32_bf16 v[12:15], v[64:67], v[12:15], 0
	v_mfma_f32_16x16x32_bf16 v[12:15], v[68:71], v[140:143], v[12:15]
	s_waitcnt lgkmcnt(6)
	v_mfma_f32_16x16x32_bf16 v[16:19], v[64:67], v[16:19], 0
	v_mfma_f32_16x16x32_bf16 v[16:19], v[68:71], v[144:147], v[16:19]
	s_waitcnt lgkmcnt(4)
	v_mfma_f32_16x16x32_bf16 v[20:23], v[64:67], v[20:23], 0
	v_mfma_f32_16x16x32_bf16 v[20:23], v[68:71], v[148:151], v[20:23]
	s_waitcnt lgkmcnt(2)
	v_mfma_f32_16x16x32_bf16 v[24:27], v[64:67], v[24:27], 0
	v_mfma_f32_16x16x32_bf16 v[24:27], v[68:71], v[152:155], v[24:27]
	s_waitcnt lgkmcnt(0)
	v_mfma_f32_16x16x32_bf16 v[28:31], v[64:67], v[28:31], 0
	v_mfma_f32_16x16x32_bf16 v[28:31], v[68:71], v[156:159], v[28:31]
	s_and_saveexec_b64 s[0:1], vcc
	s_xor_b64 s[0:1], exec, s[0:1]
	s_cbranch_execz .LBB0_91
	s_movk_i32 s2, 0x4800
	v_lshlrev_b32_e32 v83, 2, v79
	v_add3_u32 v86, v34, v32, s2
	v_add_u32_e32 v32, v80, v81
	v_lshlrev_b32_e32 v33, 3, v79
	v_sub_u32_e32 v87, v32, v83
	v_mov_b32_e32 v32, 0
	v_mov_b32_e32 v77, v82
	v_add_u32_e32 v84, 1, v45
	v_mad_u32_u24 v85, v81, s4, v33
	s_mov_b64 s[2:3], 0
	v_mov_b32_e32 v88, v83
	v_mov_b32_e32 v33, v32
	v_mov_b32_e32 v34, v32
	v_mov_b32_e32 v35, v32
	v_mov_b32_e32 v36, v32
	v_mov_b32_e32 v37, v32
	v_mov_b32_e32 v38, v32
	v_mov_b32_e32 v39, v32
	v_mov_b32_e32 v56, v32
	v_mov_b32_e32 v57, v32
	v_mov_b32_e32 v58, v32
	v_mov_b32_e32 v59, v32
	v_mov_b32_e32 v60, v32
	v_mov_b32_e32 v61, v32
	v_mov_b32_e32 v62, v32
	v_mov_b32_e32 v63, v32
	v_mov_b32_e32 v40, v32
	v_mov_b32_e32 v41, v32
	v_mov_b32_e32 v42, v32
	v_mov_b32_e32 v43, v32
	v_mov_b32_e32 v48, v32
	v_mov_b32_e32 v49, v32
	v_mov_b32_e32 v50, v32
	v_mov_b32_e32 v51, v32
	v_mov_b32_e32 v44, v32
	v_mov_b32_e32 v45, v32
	v_mov_b32_e32 v46, v32
	v_mov_b32_e32 v47, v32
	v_mov_b32_e32 v52, v32
	v_mov_b32_e32 v53, v32
	v_mov_b32_e32 v54, v32
	v_mov_b32_e32 v55, v32
	s_branch .LBB0_88
	s_nop 0
	s_nop 0
	s_nop 0
	s_nop 0
	s_nop 0
	s_nop 0
	s_nop 0
	s_nop 0
	s_nop 0
	s_nop 0
	s_nop 0
	s_nop 0
	s_nop 0
	s_nop 0
	s_nop 0

; DEV bf16_t f2bf(float f) { return (bf16_t)(cvt_pk_bf16(f, 0.f) & 0xffffu); }
; DEV float bf2f(unsigned h) { return __uint_as_float(h << 16); }
; DEV float sigmoidf_(float x) { return 1.0f / (1.0f + __expf(-x)); }
; DEV void ret_sample_item(const Params& p, int l, int item, unsigned char* smem) {
;     ...
;   {
;     const int i = w;
;     const float qd = __expf(lg * (float)(i + 1));
;     float o[2]; float ss = 0.f;
; #pragma unroll
;     for (int c = 0; c < 2; ++c) {
;       const int e = lane + c * 64;
;       float a = qd * (part[(0 * 8 + i) * 128 + e] + part[(1 * 8 + i) * 128 + e] + part[(2 * 8 + i) * 128 + e] + part[(3 * 8 + i) * 128 + e]);
;       for (int j = 0; j <= i; ++j) a += inn[i * 8 + j] * vs[j * 128 + e];
;       o[c] = a; ss += a * a;
;     }
;     ss = wave_sum(ss);
;     const float rstd = rsqrtf(ss * (1.0f / 128.0f) + 1e-6f);
; #pragma unroll
;     for (int c = 0; c < 2; ++c) {
;       bf16_t* zp = Z + (rowbase + i) * NIN + RG + h * 128 + lane + c * 64;
;       const float g = bf2f(*zp);
;       *zp = f2bf(g * sigmoidf_(g) * o[c] * rstd);
;     }
.LBB0_335:
	s_or_b64 exec, exec, s[0:1]
	v_pk_mul_f32 v[2:3], v[0:1], v[0:1]
	s_nop 0
	v_add_f32_e32 v2, v2, v3
	s_mov_b32 s0, 0x800000
	s_lshl_b32 s6, s6, 1
	v_lshl_add_u64 v[106:107], v[64:65], 0, s[6:7]
	v_lshl_add_u64 v[106:107], v[106:107], 0, v[168:169]
	global_load_ushort v108, v[106:107], off offset:2048
	global_load_ushort v109, v[106:107], off offset:2176
	v_mov_b32_e32 v3, v2
	v_mov_b32_e32 v4, v2
	s_nop 1
	v_permlane32_swap_b32_e32 v3, v4
	s_nop 0
	v_add_f32_e32 v2, v3, v4
	s_nop 0
	v_mov_b32_e32 v3, v2
	v_mov_b32_e32 v4, v2
	s_nop 1
	v_permlane16_swap_b32_e32 v3, v4
	s_nop 0
	v_add_f32_e32 v2, v3, v4
	s_nop 1
	v_add_f32_dpp v2, v2, v2 row_ror:8 row_mask:0xf bank_mask:0xf
	s_nop 1
	v_mov_b32_dpp v3, v2 row_shl:4 row_mask:0xf bank_mask:0x5
	v_mov_b32_dpp v3, v2 row_shr:4 row_mask:0xf bank_mask:0xa
	s_nop 1
	v_add_f32_e32 v2, v2, v3
	s_nop 1
	v_add_f32_dpp v2, v2, v2 quad_perm:[2,3,0,1] row_mask:0xf bank_mask:0xf
	s_nop 1
	v_add_f32_dpp v2, v2, v2 quad_perm:[1,0,3,2] row_mask:0xf bank_mask:0xf
	s_nop 0
	v_fmamk_f32 v2, v2, 0x3c000000, v170
	v_cmp_gt_f32_e32 vcc, s0, v2
	v_mul_f32_e32 v3, 0x4b800000, v2
	s_nop 0
	v_cndmask_b32_e32 v2, v2, v3, vcc
	v_rsq_f32_e32 v2, v2
	s_nop 0
	v_mul_f32_e32 v3, 0x45800000, v2
	v_cndmask_b32_e32 v4, v2, v3, vcc
	s_waitcnt vmcnt(1)
	v_lshlrev_b32_e32 v5, 16, v108
	v_mul_f32_e32 v6, 0xbfb8aa3b, v5
	v_exp_f32_e32 v6, v6
	s_nop 0
	v_add_f32_e32 v6, 1.0, v6
	v_rcp_f32_e32 v8, v6
	s_nop 0
	v_fma_f32 v9, -v6, v8, 1.0
	v_fmac_f32_e32 v8, v9, v8
	v_mov_b32_e32 v6, v8
	v_mul_f32_e32 v5, v6, v5
	v_mul_f32_e32 v0, v0, v5
	v_mul_f32_e32 v0, v4, v0
	v_cvt_pk_bf16_f32 v0, v0, s0
	global_store_short v[106:107], v0, off offset:2048
	s_waitcnt vmcnt(1)
	v_lshlrev_b32_e32 v0, 16, v109
	v_mul_f32_e32 v5, 0xbfb8aa3b, v0
	v_exp_f32_e32 v5, v5
	s_nop 0
	v_add_f32_e32 v5, 1.0, v5
	v_rcp_f32_e32 v7, v5
	s_nop 0
	v_fma_f32 v8, -v5, v7, 1.0
	v_fmac_f32_e32 v7, v8, v7
	v_mov_b32_e32 v5, v7
	v_mul_f32_e32 v0, v5, v0
	v_mul_f32_e32 v0, v1, v0
	v_mul_f32_e32 v0, v4, v0
	v_cvt_pk_bf16_f32 v0, v0, s0
	global_store_short v[106:107], v0, off offset:2176
	s_barrier

; #define PG8_STAGE(bufoff, gbase, voff) do { _Pragma("unroll") for (int _i = 0; _i < 2; ++_i) \
;     __builtin_amdgcn_global_load_lds((const unsigned*)((const char*)(gbase) + (voff)[_i]), (PG8_LAS unsigned*)(lds + (bufoff) + ldsw + _i * 8192), 16, 0, 0); } while (0)
; #define PG8_WAIT_V(n) asm volatile("s_waitcnt vmcnt(" #n ")" ::: "memory")
; #define PG8_BAR __builtin_amdgcn_s_barrier()
; template <class Epi, bool SEQ>
; DEV void gemm_phase(PG8_LAS unsigned char* lds, const Gemm g, const Epi& E) {
;     ...
;   for (int i = 0; i < 2; ++i) { int R, C; stage_rc(tid * 16 + i * 8192, R, C); const int Rb = Epi::PERM ? ((R & ~31) + perm32(R & 31)) : R;
;     voffA[i] = (unsigned)(R * g.lda + C) * 2u; voffB[i] = (unsigned)(Rb * g.ldb + C) * 2u; }
;   const size_t kstep = (size_t)(BK * 2);
;   const size_t hstepA = (size_t)HALF * g.lda * 2, hstepB = (size_t)HALF * g.ldb * 2;
;   const size_t tstepA = 2 * hstepA, tstepB = 2 * hstepB;
;   const unsigned ldsw = (unsigned)wid * 1024u;
;   const int aoff = lds_byte(wr * 64 + fr, fq * 8), boff = lds_byte(wc * 32 + fr, fq * 8);
;     ...
;   PG8_STAGE(PG8_SB(0, 0), cB, voffB); PG8_STAGE(PG8_SB(0, 1), cB + hstepB, voffB); PG8_STAGE(PG8_SA(0, 0), cA, voffA); PG8_STAGE(PG8_SA(0, 1), cA + hstepA, voffA);
;   if (wr == 1) PG8_BAR;
;   PG8_WAIT_V(2); PG8_BAR;
;   PG8_STAGE(PG8_SB(1, 0), cB + kstep, voffB); PG8_STAGE(PG8_SA(1, 0), cA + kstep, voffA); PG8_STAGE(PG8_SB(1, 1), cB + hstepB + kstep, voffB);
;   PG8_WAIT_V(6); PG8_BAR;
.LBB0_489:
	s_lshl_b32 s4, s4, 5
	s_and_b32 s9, s4, 0x60
	s_add_i32 m0, s35, 0x18000
	v_lshl_add_u64 v[6:7], v[6:7], 0, s[10:11]
	s_lshl_b32 s8, s3, 13
	s_lshl_b32 s12, s9, 7
	s_waitcnt vmcnt(2)
	s_barrier
	global_load_lds_dwordx4 v[6:7], off
	v_lshl_add_u64 v[4:5], v[4:5], 0, s[10:11]
	s_add_i32 m0, s35, 0x1a000
	s_add_i32 s39, s35, 0x8000
	s_add_i32 s40, s35, 0xa000
	global_load_lds_dwordx4 v[4:5], off
	v_lshl_add_u64 v[0:1], v[0:1], 0, s[10:11]
	s_mov_b32 m0, s39
	s_add_u32 s4, s20, 0x40080
	global_load_lds_dwordx4 v[0:1], off
	v_lshl_add_u64 v[0:1], v[2:3], 0, s[10:11]
	s_mov_b32 m0, s40
	s_addc_u32 s5, s21, 0
	global_load_lds_dwordx4 v[0:1], off
	s_add_i32 m0, s35, 0x1c000
	v_lshl_add_u64 v[0:1], s[4:5], 0, v[168:169]
	global_load_lds_dwordx4 v[0:1], off
	v_lshl_add_u64 v[0:1], s[4:5], 0, v[132:133]
	s_add_i32 m0, s35, 0x1e000
	s_cmpk_lt_u32 s2, 0x100
	global_load_lds_dwordx4 v[0:1], off
	v_lshrrev_b32_e32 v1, 1, v8
	v_and_b32_e32 v1, 24, v1
	v_and_b32_e32 v0, 15, v8
	v_lshlrev_b32_e32 v2, 1, v1
	v_lshl_or_b32 v138, s3, 6, v0
	v_lshl_or_b32 v0, v0, 6, v2
	v_lshlrev_b32_e32 v2, 2, v8
	v_and_b32_e32 v2, 32, v2
	v_bitop3_b32 v3, v0, s8, v2 bitop3:0xde
	v_bitop3_b32 v139, v0, s12, v2 bitop3:0xde
	v_lshlrev_b32_e32 v0, 14, v9
	v_and_b32_e32 v0, 0xffff8000, v0
	v_or_b32_e32 v140, s9, v1
	v_lshl_add_u32 v0, v10, 11, v0
	v_and_b32_e32 v1, 1, v9
	v_lshl_or_b32 v0, v1, 6, v0
	v_lshl_add_u32 v134, v11, 1, v0
	v_lshlrev_b32_e32 v0, 14, v12
	v_and_b32_e32 v0, 0xffff8000, v0
	s_waitcnt vmcnt(6)
	v_lshl_add_u32 v0, v13, 11, v0
	v_and_b32_e32 v1, 1, v12
	v_lshl_or_b32 v0, v1, 6, v0
	s_cselect_b64 s[2:3], -1, 0
	v_mov_b32_e32 v135, v169
	v_lshl_add_u32 v136, v14, 1, v0
	v_mov_b32_e32 v137, v169
	s_mov_b32 s41, 0
	v_add_u32_e32 v141, 0, v3
	s_barrier
	s_branch .LBB0_492
	s_nop 0
	s_nop 0
	s_nop 0
	s_nop 0
	s_nop 0
	s_nop 0
	s_nop 0
	s_nop 0
